# dropped the grid sync before each group's layer-0 input RMSNorm (it reads only kernel inputs)
# speedup vs baseline: 1.0435x; 1.0022x over previous
; __host__ __device__ __forceinline__ bool phase_needs_sync(int ph) {
;     if (ph == 0) return false;
;     const int r = (ph - 1) % PH_PER_GROUP; if (r == DEPTH * PH_PER_LAYER) return true;
;     const int st = r % PH_PER_LAYER;
;     return !(st == ST_ICLR || st == ST_GATE || st == ST_Q || st == ST_KV || st == ST_SCAN || st == ST_OB);
; }
; __global__ void __launch_bounds__(NTHR, 2) mk_fwd(Params Punused) {
;     ...
;     for (int ph = lo; ph < hi;) {
;     ...
;         if (ph > lo && rep == 0 && phase_needs_sync(ph)) { if (ph == 1) cg::this_grid().sync(); else xcd_barrier(bar); }
;         else if (ph > lo) __syncthreads();
.LBB0_8:
	s_cmp_le_i32 s85, s94
	s_cbranch_scc1 .LBB0_90
	s_cmp_eq_u32 s85, 0
	s_cbranch_scc1 .LBB0_14
	s_add_i32 s0, s85, -1
	s_mul_hi_i32 s1, s0, 0xea0ea0eb
	s_add_i32 s1, s1, s0
	s_lshr_b32 s4, s1, 31
	s_ashr_i32 s1, s1, 5
	s_add_i32 s1, s1, s4
	s_mul_i32 s1, s1, 35
	s_sub_i32 s0, s0, s1
	s_cmp_eq_u32 s0, 0
	s_cbranch_scc1 .LBB0_14
	s_cmp_lg_u32 s0, 34
	s_cbranch_scc0 .LBB0_15
	s_mul_i32 s1, s0, 0x79
	s_sext_i32_i16 s4, s1
	s_ashr_i32 s4, s4, 11
	s_bfe_u32 s1, s1, 0x1000f
	s_add_i32 s1, s4, s1
	s_mul_i32 s1, s1, 17
	s_sub_i32 s0, s0, s1
	s_and_b32 s1, s0, 0xfc
	s_cmp_lg_u32 s1, 4
	s_cbranch_scc0 .LBB0_16
	s_waitcnt lgkmcnt(0)
	s_and_b32 s8, s0, 0xff
	s_cmp_lt_i32 s8, 12
	s_cbranch_scc1 .LBB0_17
	s_and_b32 s4, 0xffff, s8
	s_cmp_lg_u32 s4, 12
	s_mov_b64 s[0:1], -1
	s_cselect_b64 s[4:5], -1, 0
	s_cbranch_execz .LBB0_18
	s_branch .LBB0_19
